# tabB_lat table by hand (paired dword stores) with 8 consecutive items per block so bank-conflicted rows are spread over blocks
# speedup vs baseline: 1.1287x; 1.0030x over previous
.LBB0_169:
	s_or_b64 exec, exec, s[2:3]
	s_load_dwordx16 s[16:31], s[0:1], 0x40
	s_mul_hi_u32 s0, s50, 0x140
	s_mul_i32 s0, s0, s49
	s_sub_i32 s0, 0x140, s0
	s_sub_i32 s1, s0, s49
	s_cmp_ge_u32 s0, s49
	s_cselect_b32 s0, s1, s0
	s_sub_i32 s1, s0, s49
	s_waitcnt lgkmcnt(0)
	v_writelane_b32 v253, s16, 18
	s_cmp_ge_u32 s0, s49
	s_cselect_b32 s0, s1, s0
	v_writelane_b32 v253, s17, 19
	s_add_i32 s14, s14, s84
	v_writelane_b32 v253, s18, 20
	s_sub_i32 s0, s14, s0
	v_writelane_b32 v253, s19, 21
	s_ashr_i32 s4, s0, 31
	s_abs_i32 s0, s0
	v_writelane_b32 v253, s20, 22
	s_mul_hi_u32 s1, s0, s50
	v_writelane_b32 v253, s21, 23
	s_mul_i32 s1, s1, s49
	v_writelane_b32 v253, s22, 24
	s_sub_i32 s0, s0, s1
	v_writelane_b32 v253, s23, 25
	s_sub_i32 s1, s0, s49
	v_writelane_b32 v253, s24, 26
	s_cmp_ge_u32 s0, s49
	v_writelane_b32 v253, s25, 27
	s_cselect_b32 s0, s1, s0
	v_writelane_b32 v253, s26, 28
	s_sub_i32 s1, s0, s49
	v_writelane_b32 v253, s27, 29
	s_cmp_ge_u32 s0, s49
	v_writelane_b32 v253, s28, 30
	s_cselect_b32 s0, s1, s0
	v_writelane_b32 v253, s29, 31
	s_xor_b32 s5, s0, s4
	v_writelane_b32 v253, s30, 32
	s_sub_i32 s2, s5, s4
	v_writelane_b32 v253, s31, 33
	s_movk_i32 s101, 0x107f
	s_cmpk_eq_i32 s84, 0x200
	s_cbranch_scc0 .Ltab_keep
	s_movk_i32 s101, 0x7f
.Ltab_keep:
	s_cmp_gt_i32 s2, s101
	s_barrier
	s_cbranch_scc1 .LBB0_180
	v_and_b32_e32 v0, 32, v2
	v_cmp_eq_u32_e64 s[0:1], 0, v0
	v_lshl_add_u32 v0, s5, 11, v4
	s_lshl_b32 s4, s4, 11
	v_ashrrev_i32_e32 v5, 31, v4
	s_mov_b32 s3, 0
	s_addk_i32 s2, 0xff80
	v_subrev_u32_e32 v6, s4, v0
	s_lshl_b32 s12, s84, 11
	s_mov_b32 s13, 0x10000
	v_mov_b32_e32 v7, 3
	s_branch .LBB0_172
.LBB0_171:
	s_lshl_b64 s[4:5], s[8:9], 12
	s_add_u32 s4, s6, s4
	s_addc_u32 s5, s7, s5
	s_add_i32 s2, s2, s84
	v_lshl_add_u64 v[8:9], v[4:5], 1, s[4:5]
	s_add_i32 s4, s2, 0x80
	s_cmp_gt_i32 s4, s101
	v_add_u32_e32 v6, s12, v6
	global_store_dwordx4 v[8:9], v[0:3], off
	s_cbranch_scc1 .LBB0_180

.Lwt_fast:
	v_and_b32_e32 v200, 63, v176
	v_lshrrev_b32_e32 v201, 6, v176
	v_lshl_add_u32 v200, v201, 9, v200
	v_add_u32_e32 v202, 0, v200
	v_lshlrev_b32_e32 v210, 1, v202
	v_add_u32_e32 v203, 64, v200
	v_lshlrev_b32_e32 v211, 1, v203
	v_add_u32_e32 v204, 128, v200
	v_lshlrev_b32_e32 v212, 1, v204
	v_add_u32_e32 v205, 192, v200
	v_lshlrev_b32_e32 v213, 1, v205
	v_add_u32_e32 v206, 256, v200
	v_lshlrev_b32_e32 v214, 1, v206
	v_add_u32_e32 v207, 320, v200
	v_lshlrev_b32_e32 v215, 1, v207
	v_add_u32_e32 v208, 384, v200
	v_lshlrev_b32_e32 v216, 1, v208
	v_add_u32_e32 v209, 448, v200
	v_lshlrev_b32_e32 v217, 1, v209
	v_readlane_b32 s4, v252, 6
	v_readlane_b32 s5, v252, 7
	s_lshl_b32 s0, s94, 3
.Ltb_loop:
	s_lshr_b32 s1, s0, 1
	s_and_b32 s2, s0, 1
	s_lshl_b32 s3, s2, 2
	s_lshl_b32 s6, s2, 31
	s_lshl_b32 s7, s0, 12
	s_add_u32 s8, s4, s7
	s_addc_u32 s9, s5, 0
	v_mul_u32_u24_e32 v218, s1, v202
	v_and_b32_e32 v218, 0x7ff, v218
	v_lshl_add_u32 v218, v218, 3, s3
	ds_read_b32 v226, v218
	v_mul_u32_u24_e32 v219, s1, v203
	v_and_b32_e32 v219, 0x7ff, v219
	v_lshl_add_u32 v219, v219, 3, s3
	ds_read_b32 v227, v219
	v_mul_u32_u24_e32 v220, s1, v204
	v_and_b32_e32 v220, 0x7ff, v220
	v_lshl_add_u32 v220, v220, 3, s3
	ds_read_b32 v228, v220
	v_mul_u32_u24_e32 v221, s1, v205
	v_and_b32_e32 v221, 0x7ff, v221
	v_lshl_add_u32 v221, v221, 3, s3
	ds_read_b32 v229, v221
	v_mul_u32_u24_e32 v222, s1, v206
	v_and_b32_e32 v222, 0x7ff, v222
	v_lshl_add_u32 v222, v222, 3, s3
	ds_read_b32 v230, v222
	v_mul_u32_u24_e32 v223, s1, v207
	v_and_b32_e32 v223, 0x7ff, v223
	v_lshl_add_u32 v223, v223, 3, s3
	ds_read_b32 v231, v223
	v_mul_u32_u24_e32 v224, s1, v208
	v_and_b32_e32 v224, 0x7ff, v224
	v_lshl_add_u32 v224, v224, 3, s3
	ds_read_b32 v232, v224
	v_mul_u32_u24_e32 v225, s1, v209
	v_and_b32_e32 v225, 0x7ff, v225
	v_lshl_add_u32 v225, v225, 3, s3
	ds_read_b32 v233, v225
	s_waitcnt lgkmcnt(0)
	v_xor_b32_e32 v226, s6, v226
	v_xor_b32_e32 v227, s6, v227
	v_xor_b32_e32 v228, s6, v228
	v_xor_b32_e32 v229, s6, v229
	v_xor_b32_e32 v230, s6, v230
	v_xor_b32_e32 v231, s6, v231
	v_xor_b32_e32 v232, s6, v232
	v_xor_b32_e32 v233, s6, v233
	s_nop 1
	v_mov_b32_dpp v234, v226 quad_perm:[1,0,3,2] row_mask:0xf bank_mask:0xf
	v_mov_b32_dpp v235, v227 quad_perm:[1,0,3,2] row_mask:0xf bank_mask:0xf
	v_mov_b32_dpp v236, v228 quad_perm:[1,0,3,2] row_mask:0xf bank_mask:0xf
	v_mov_b32_dpp v237, v229 quad_perm:[1,0,3,2] row_mask:0xf bank_mask:0xf
	v_mov_b32_dpp v238, v230 quad_perm:[1,0,3,2] row_mask:0xf bank_mask:0xf
	v_mov_b32_dpp v239, v231 quad_perm:[1,0,3,2] row_mask:0xf bank_mask:0xf
	v_mov_b32_dpp v240, v232 quad_perm:[1,0,3,2] row_mask:0xf bank_mask:0xf
	v_mov_b32_dpp v241, v233 quad_perm:[1,0,3,2] row_mask:0xf bank_mask:0xf
	v_cvt_pk_bf16_f32 v226, v226, v234
	v_cvt_pk_bf16_f32 v227, v227, v235
	v_cvt_pk_bf16_f32 v228, v228, v236
	v_cvt_pk_bf16_f32 v229, v229, v237
	v_cvt_pk_bf16_f32 v230, v230, v238
	v_cvt_pk_bf16_f32 v231, v231, v239
	v_cvt_pk_bf16_f32 v232, v232, v240
	v_cvt_pk_bf16_f32 v233, v233, v241
	s_mov_b32 exec_lo, 0x55555555
	s_mov_b32 exec_hi, 0x55555555
	global_store_dword v210, v226, s[8:9]
	global_store_dword v211, v227, s[8:9]
	global_store_dword v212, v228, s[8:9]
	global_store_dword v213, v229, s[8:9]
	global_store_dword v214, v230, s[8:9]
	global_store_dword v215, v231, s[8:9]
	global_store_dword v216, v232, s[8:9]
	global_store_dword v217, v233, s[8:9]
	s_mov_b64 exec, -1
	s_add_i32 s0, s0, 1
	s_and_b32 s1, s0, 7
	s_cmp_lg_u32 s1, 0
	s_cbranch_scc1 .Ltb_loop
	s_barrier
	v_and_b32_e32 v120, 63, v176
	v_lshrrev_b32_e32 v121, 6, v176
	v_lshlrev_b32_e32 v122, 2, v120
	v_mul_u32_u24_e32 v123, 65, v120
	v_add_lshl_u32 v123, v123, v121, 2
	v_lshrrev_b32_e32 v129, 2, v176
	v_mul_u32_u24_e32 v124, 65, v129
	v_lshlrev_b32_e32 v125, 11, v129
	v_and_b32_e32 v129, 3, v176
	v_lshl_add_u32 v124, v129, 4, v124
	v_lshlrev_b32_e32 v124, 2, v124
	v_lshl_add_u32 v125, v129, 5, v125
	v_add_u32_e32 v127, 0x4100, v123
	v_add_u32_e32 v128, 0x4100, v124
	s_mov_b32 s1, 0
	s_mov_b32 s0, s94
	s_cmpk_lt_u32 s94, 0x150
	s_cbranch_scc1 .Lwt_start
	s_sub_i32 s0, s94, 0x150
	s_mul_i32 s0, s0, 3
	s_addk_i32 s0, 0x150
